# P7 epilogue de-serialised: half-0 residual loads issued before the DPP permutes, half-1 loads issued before half-0 stores with a counted vmcnt(16)
# baseline (speedup 1.0000x reference)
;     __device__ __forceinline__ void operator()(const f32x4 (&acc)[2][2][4][2], const pg8::Unit& u, int wr, int wc, int fr, int fq) const {
;         const int row0 = u.pm * 256 + wr * 64 + fr; const int colb = u.pn * 256 + 32 * wc + 8 * fq;
;         if (u.nt == 0) {
; #pragma unroll
;             for (int ai = 0; ai < 2; ++ai) {
;                 f32x4 xv[4][2][2];
; #pragma unroll
;                 for (int m = 0; m < 4; ++m)
; #pragma unroll
;                     for (int bj = 0; bj < 2; ++bj) { const float* xr = out + (size_t)(row0 + ai * 128 + m * 16) * DM + colb + 128 * bj; xv[m][bj][0] = *(const f32x4*)xr; xv[m][bj][1] = *(const f32x4*)(xr + 4); }
; #pragma unroll
;                 for (int m = 0; m < 4; ++m) {
;                     float* orow = out + (size_t)(row0 + ai * 128 + m * 16) * DM;
; #pragma unroll
;                     for (int bj = 0; bj < 2; ++bj) {
;                         const int col = colb + 128 * bj;
;                         *(f32x4*)(orow + col) = acc[ai][bj][m][0] + xv[m][bj][0]; *(f32x4*)(orow + col + 4) = acc[ai][bj][m][1] + xv[m][bj][1];
;                     }
;                 }
;             }
.LBB0_809:
	v_readlane_b32 s18, v254, 30
	v_readlane_b32 s19, v254, 31
	v_bfe_u32 v150, v148, 3, 1
	v_and_b32_e32 v148, 0xfffffff7, v148
	v_lshl_add_u32 v142, v150, 2, v142
	v_lshlrev_b64 v[142:143], 2, v[142:143]
	v_lshlrev_b64 v[146:147], 13, v[148:149]
	v_lshl_add_u64 v[144:145], s[18:19], 0, v[142:143]
	v_lshl_add_u64 v[146:147], v[144:145], 0, v[146:147]
	s_mov_b32 s5, 0
	s_mov_b32 s4, 0x0
	v_lshl_add_u64 v[224:225], v[146:147], 0, s[4:5]
	global_load_dwordx4 v[160:163], v[224:225], off
	global_load_dwordx4 v[168:171], v[224:225], off offset:512
	s_mov_b32 s4, 0x10000
	v_lshl_add_u64 v[226:227], v[146:147], 0, s[4:5]
	global_load_dwordx4 v[164:167], v[226:227], off
	global_load_dwordx4 v[172:175], v[226:227], off offset:512
	s_mov_b32 s4, 0x20000
	v_lshl_add_u64 v[224:225], v[146:147], 0, s[4:5]
	global_load_dwordx4 v[176:179], v[224:225], off
	global_load_dwordx4 v[184:187], v[224:225], off offset:512
	s_mov_b32 s4, 0x30000
	v_lshl_add_u64 v[226:227], v[146:147], 0, s[4:5]
	global_load_dwordx4 v[180:183], v[226:227], off
	global_load_dwordx4 v[190:193], v[226:227], off offset:512
	s_mov_b32 s4, 0x40000
	v_lshl_add_u64 v[224:225], v[146:147], 0, s[4:5]
	global_load_dwordx4 v[194:197], v[224:225], off
	global_load_dwordx4 v[202:205], v[224:225], off offset:512
	s_mov_b32 s4, 0x50000
	v_lshl_add_u64 v[226:227], v[146:147], 0, s[4:5]
	global_load_dwordx4 v[198:201], v[226:227], off
	global_load_dwordx4 v[206:209], v[226:227], off offset:512
	s_mov_b32 s4, 0x60000
	v_lshl_add_u64 v[224:225], v[146:147], 0, s[4:5]
	global_load_dwordx4 v[210:213], v[224:225], off
	global_load_dwordx4 v[218:221], v[224:225], off offset:512
	s_mov_b32 s4, 0x70000
	v_lshl_add_u64 v[226:227], v[146:147], 0, s[4:5]
	global_load_dwordx4 v[214:217], v[226:227], off
	global_load_dwordx4 v[150:153], v[226:227], off offset:512
	v_mov_b32_e32 v222, v124
	v_mov_b32_e32 v223, v125
	v_mov_b32_e32 v224, v126
	v_mov_b32_e32 v225, v127
	v_mov_b32_dpp v124, v120 row_ror:8 row_mask:0xf bank_mask:0xc
	v_mov_b32_dpp v125, v121 row_ror:8 row_mask:0xf bank_mask:0xc
	v_mov_b32_dpp v126, v122 row_ror:8 row_mask:0xf bank_mask:0xc
	v_mov_b32_dpp v127, v123 row_ror:8 row_mask:0xf bank_mask:0xc
	v_mov_b32_dpp v120, v222 row_ror:8 row_mask:0xf bank_mask:0x3
	v_mov_b32_dpp v121, v223 row_ror:8 row_mask:0xf bank_mask:0x3
	v_mov_b32_dpp v122, v224 row_ror:8 row_mask:0xf bank_mask:0x3
	v_mov_b32_dpp v123, v225 row_ror:8 row_mask:0xf bank_mask:0x3
	v_mov_b32_e32 v142, v116
	v_mov_b32_e32 v143, v117
	v_mov_b32_e32 v144, v118
	v_mov_b32_e32 v145, v119
	v_mov_b32_dpp v116, v112 row_ror:8 row_mask:0xf bank_mask:0xc
	v_mov_b32_dpp v117, v113 row_ror:8 row_mask:0xf bank_mask:0xc
	v_mov_b32_dpp v118, v114 row_ror:8 row_mask:0xf bank_mask:0xc
	v_mov_b32_dpp v119, v115 row_ror:8 row_mask:0xf bank_mask:0xc
	v_mov_b32_dpp v112, v142 row_ror:8 row_mask:0xf bank_mask:0x3
	v_mov_b32_dpp v113, v143 row_ror:8 row_mask:0xf bank_mask:0x3
	v_mov_b32_dpp v114, v144 row_ror:8 row_mask:0xf bank_mask:0x3
	v_mov_b32_dpp v115, v145 row_ror:8 row_mask:0xf bank_mask:0x3
	v_mov_b32_e32 v222, v108
	v_mov_b32_e32 v223, v109
	v_mov_b32_e32 v224, v110
	v_mov_b32_e32 v225, v111
	v_mov_b32_dpp v108, v104 row_ror:8 row_mask:0xf bank_mask:0xc
	v_mov_b32_dpp v109, v105 row_ror:8 row_mask:0xf bank_mask:0xc
	v_mov_b32_dpp v110, v106 row_ror:8 row_mask:0xf bank_mask:0xc
	v_mov_b32_dpp v111, v107 row_ror:8 row_mask:0xf bank_mask:0xc
	v_mov_b32_dpp v104, v222 row_ror:8 row_mask:0xf bank_mask:0x3
	v_mov_b32_dpp v105, v223 row_ror:8 row_mask:0xf bank_mask:0x3
	v_mov_b32_dpp v106, v224 row_ror:8 row_mask:0xf bank_mask:0x3
	v_mov_b32_dpp v107, v225 row_ror:8 row_mask:0xf bank_mask:0x3
	v_mov_b32_e32 v142, v100
	v_mov_b32_e32 v143, v101
	v_mov_b32_e32 v144, v102
	v_mov_b32_e32 v145, v103
	v_mov_b32_dpp v100, v96 row_ror:8 row_mask:0xf bank_mask:0xc
	v_mov_b32_dpp v101, v97 row_ror:8 row_mask:0xf bank_mask:0xc
	v_mov_b32_dpp v102, v98 row_ror:8 row_mask:0xf bank_mask:0xc
	v_mov_b32_dpp v103, v99 row_ror:8 row_mask:0xf bank_mask:0xc
	v_mov_b32_dpp v96, v142 row_ror:8 row_mask:0xf bank_mask:0x3
	v_mov_b32_dpp v97, v143 row_ror:8 row_mask:0xf bank_mask:0x3
	v_mov_b32_dpp v98, v144 row_ror:8 row_mask:0xf bank_mask:0x3
	v_mov_b32_dpp v99, v145 row_ror:8 row_mask:0xf bank_mask:0x3
	v_mov_b32_e32 v222, v92
	v_mov_b32_e32 v223, v93
	v_mov_b32_e32 v224, v94
	v_mov_b32_e32 v225, v95
	v_mov_b32_dpp v92, v88 row_ror:8 row_mask:0xf bank_mask:0xc
	v_mov_b32_dpp v93, v89 row_ror:8 row_mask:0xf bank_mask:0xc
	v_mov_b32_dpp v94, v90 row_ror:8 row_mask:0xf bank_mask:0xc
	v_mov_b32_dpp v95, v91 row_ror:8 row_mask:0xf bank_mask:0xc
	v_mov_b32_dpp v88, v222 row_ror:8 row_mask:0xf bank_mask:0x3
	v_mov_b32_dpp v89, v223 row_ror:8 row_mask:0xf bank_mask:0x3
	v_mov_b32_dpp v90, v224 row_ror:8 row_mask:0xf bank_mask:0x3
	v_mov_b32_dpp v91, v225 row_ror:8 row_mask:0xf bank_mask:0x3
	v_mov_b32_e32 v142, v84
	v_mov_b32_e32 v143, v85
	v_mov_b32_e32 v144, v86
	v_mov_b32_e32 v145, v87
	v_mov_b32_dpp v84, v80 row_ror:8 row_mask:0xf bank_mask:0xc
	v_mov_b32_dpp v85, v81 row_ror:8 row_mask:0xf bank_mask:0xc
	v_mov_b32_dpp v86, v82 row_ror:8 row_mask:0xf bank_mask:0xc
	v_mov_b32_dpp v87, v83 row_ror:8 row_mask:0xf bank_mask:0xc
	v_mov_b32_dpp v80, v142 row_ror:8 row_mask:0xf bank_mask:0x3
	v_mov_b32_dpp v81, v143 row_ror:8 row_mask:0xf bank_mask:0x3
	v_mov_b32_dpp v82, v144 row_ror:8 row_mask:0xf bank_mask:0x3
	v_mov_b32_dpp v83, v145 row_ror:8 row_mask:0xf bank_mask:0x3
	v_mov_b32_e32 v222, v76
	v_mov_b32_e32 v223, v77
	v_mov_b32_e32 v224, v78
	v_mov_b32_e32 v225, v79
	v_mov_b32_dpp v76, v72 row_ror:8 row_mask:0xf bank_mask:0xc
	v_mov_b32_dpp v77, v73 row_ror:8 row_mask:0xf bank_mask:0xc
;     __device__ __forceinline__ void operator()(const f32x4 (&acc)[2][2][4][2], const pg8::Unit& u, int wr, int wc, int fr, int fq) const {
;         const int row0 = u.pm * 256 + wr * 64 + fr; const int colb = u.pn * 256 + 32 * wc + 8 * fq;
;         if (u.nt == 0) {
; #pragma unroll
;             for (int ai = 0; ai < 2; ++ai) {
;                 f32x4 xv[4][2][2];
; #pragma unroll
;                 for (int m = 0; m < 4; ++m)
; #pragma unroll
;                     for (int bj = 0; bj < 2; ++bj) { const float* xr = out + (size_t)(row0 + ai * 128 + m * 16) * DM + colb + 128 * bj; xv[m][bj][0] = *(const f32x4*)xr; xv[m][bj][1] = *(const f32x4*)(xr + 4); }
; #pragma unroll
;                 for (int m = 0; m < 4; ++m) {
;                     float* orow = out + (size_t)(row0 + ai * 128 + m * 16) * DM;
; #pragma unroll
;                     for (int bj = 0; bj < 2; ++bj) {
;                         const int col = colb + 128 * bj;
;                         *(f32x4*)(orow + col) = acc[ai][bj][m][0] + xv[m][bj][0]; *(f32x4*)(orow + col + 4) = acc[ai][bj][m][1] + xv[m][bj][1];
;                     }
;                 }
;             }
	v_mov_b32_dpp v78, v74 row_ror:8 row_mask:0xf bank_mask:0xc
	v_mov_b32_dpp v79, v75 row_ror:8 row_mask:0xf bank_mask:0xc
	v_mov_b32_dpp v72, v222 row_ror:8 row_mask:0xf bank_mask:0x3
	v_mov_b32_dpp v73, v223 row_ror:8 row_mask:0xf bank_mask:0x3
	v_mov_b32_dpp v74, v224 row_ror:8 row_mask:0xf bank_mask:0x3
	v_mov_b32_dpp v75, v225 row_ror:8 row_mask:0xf bank_mask:0x3
	v_mov_b32_e32 v142, v68
	v_mov_b32_e32 v143, v69
	v_mov_b32_e32 v144, v70
	v_mov_b32_e32 v145, v71
	v_mov_b32_dpp v68, v64 row_ror:8 row_mask:0xf bank_mask:0xc
	v_mov_b32_dpp v69, v65 row_ror:8 row_mask:0xf bank_mask:0xc
	v_mov_b32_dpp v70, v66 row_ror:8 row_mask:0xf bank_mask:0xc
	v_mov_b32_dpp v71, v67 row_ror:8 row_mask:0xf bank_mask:0xc
	v_mov_b32_dpp v64, v142 row_ror:8 row_mask:0xf bank_mask:0x3
	v_mov_b32_dpp v65, v143 row_ror:8 row_mask:0xf bank_mask:0x3
	v_mov_b32_dpp v66, v144 row_ror:8 row_mask:0xf bank_mask:0x3
	v_mov_b32_dpp v67, v145 row_ror:8 row_mask:0xf bank_mask:0x3
	v_mov_b32_e32 v222, v60
	v_mov_b32_e32 v223, v61
	v_mov_b32_e32 v224, v62
	v_mov_b32_e32 v225, v63
	v_mov_b32_dpp v60, v56 row_ror:8 row_mask:0xf bank_mask:0xc
	v_mov_b32_dpp v61, v57 row_ror:8 row_mask:0xf bank_mask:0xc
	v_mov_b32_dpp v62, v58 row_ror:8 row_mask:0xf bank_mask:0xc
	v_mov_b32_dpp v63, v59 row_ror:8 row_mask:0xf bank_mask:0xc
	v_mov_b32_dpp v56, v222 row_ror:8 row_mask:0xf bank_mask:0x3
	v_mov_b32_dpp v57, v223 row_ror:8 row_mask:0xf bank_mask:0x3
	v_mov_b32_dpp v58, v224 row_ror:8 row_mask:0xf bank_mask:0x3
	v_mov_b32_dpp v59, v225 row_ror:8 row_mask:0xf bank_mask:0x3
	v_mov_b32_e32 v142, v52
	v_mov_b32_e32 v143, v53
	v_mov_b32_e32 v144, v54
	v_mov_b32_e32 v145, v55
	v_mov_b32_dpp v52, v48 row_ror:8 row_mask:0xf bank_mask:0xc
	v_mov_b32_dpp v53, v49 row_ror:8 row_mask:0xf bank_mask:0xc
	v_mov_b32_dpp v54, v50 row_ror:8 row_mask:0xf bank_mask:0xc
	v_mov_b32_dpp v55, v51 row_ror:8 row_mask:0xf bank_mask:0xc
	v_mov_b32_dpp v48, v142 row_ror:8 row_mask:0xf bank_mask:0x3
	v_mov_b32_dpp v49, v143 row_ror:8 row_mask:0xf bank_mask:0x3
	v_mov_b32_dpp v50, v144 row_ror:8 row_mask:0xf bank_mask:0x3
	v_mov_b32_dpp v51, v145 row_ror:8 row_mask:0xf bank_mask:0x3
	v_mov_b32_e32 v222, v44
	v_mov_b32_e32 v223, v45
	v_mov_b32_e32 v224, v46
	v_mov_b32_e32 v225, v47
	v_mov_b32_dpp v44, v40 row_ror:8 row_mask:0xf bank_mask:0xc
	v_mov_b32_dpp v45, v41 row_ror:8 row_mask:0xf bank_mask:0xc
	v_mov_b32_dpp v46, v42 row_ror:8 row_mask:0xf bank_mask:0xc
	v_mov_b32_dpp v47, v43 row_ror:8 row_mask:0xf bank_mask:0xc
	v_mov_b32_dpp v40, v222 row_ror:8 row_mask:0xf bank_mask:0x3
	v_mov_b32_dpp v41, v223 row_ror:8 row_mask:0xf bank_mask:0x3
	v_mov_b32_dpp v42, v224 row_ror:8 row_mask:0xf bank_mask:0x3
	v_mov_b32_dpp v43, v225 row_ror:8 row_mask:0xf bank_mask:0x3
	v_mov_b32_e32 v142, v36
	v_mov_b32_e32 v143, v37
	v_mov_b32_e32 v144, v38
	v_mov_b32_e32 v145, v39
	v_mov_b32_dpp v36, v32 row_ror:8 row_mask:0xf bank_mask:0xc
	v_mov_b32_dpp v37, v33 row_ror:8 row_mask:0xf bank_mask:0xc
	v_mov_b32_dpp v38, v34 row_ror:8 row_mask:0xf bank_mask:0xc
	v_mov_b32_dpp v39, v35 row_ror:8 row_mask:0xf bank_mask:0xc
	v_mov_b32_dpp v32, v142 row_ror:8 row_mask:0xf bank_mask:0x3
	v_mov_b32_dpp v33, v143 row_ror:8 row_mask:0xf bank_mask:0x3
	v_mov_b32_dpp v34, v144 row_ror:8 row_mask:0xf bank_mask:0x3
	v_mov_b32_dpp v35, v145 row_ror:8 row_mask:0xf bank_mask:0x3
	v_mov_b32_e32 v222, v28
	v_mov_b32_e32 v223, v29
	v_mov_b32_e32 v224, v30
	v_mov_b32_e32 v225, v31
	v_mov_b32_dpp v28, v24 row_ror:8 row_mask:0xf bank_mask:0xc
	v_mov_b32_dpp v29, v25 row_ror:8 row_mask:0xf bank_mask:0xc
	v_mov_b32_dpp v30, v26 row_ror:8 row_mask:0xf bank_mask:0xc
	v_mov_b32_dpp v31, v27 row_ror:8 row_mask:0xf bank_mask:0xc
	v_mov_b32_dpp v24, v222 row_ror:8 row_mask:0xf bank_mask:0x3
	v_mov_b32_dpp v25, v223 row_ror:8 row_mask:0xf bank_mask:0x3
	v_mov_b32_dpp v26, v224 row_ror:8 row_mask:0xf bank_mask:0x3
	v_mov_b32_dpp v27, v225 row_ror:8 row_mask:0xf bank_mask:0x3
	v_mov_b32_e32 v142, v20
	v_mov_b32_e32 v143, v21
	v_mov_b32_e32 v144, v22
	v_mov_b32_e32 v145, v23
	v_mov_b32_dpp v20, v16 row_ror:8 row_mask:0xf bank_mask:0xc
	v_mov_b32_dpp v21, v17 row_ror:8 row_mask:0xf bank_mask:0xc
	v_mov_b32_dpp v22, v18 row_ror:8 row_mask:0xf bank_mask:0xc
	v_mov_b32_dpp v23, v19 row_ror:8 row_mask:0xf bank_mask:0xc
	v_mov_b32_dpp v16, v142 row_ror:8 row_mask:0xf bank_mask:0x3
	v_mov_b32_dpp v17, v143 row_ror:8 row_mask:0xf bank_mask:0x3
	v_mov_b32_dpp v18, v144 row_ror:8 row_mask:0xf bank_mask:0x3
	v_mov_b32_dpp v19, v145 row_ror:8 row_mask:0xf bank_mask:0x3
	v_mov_b32_e32 v222, v12
	v_mov_b32_e32 v223, v13
	v_mov_b32_e32 v224, v14
	v_mov_b32_e32 v225, v15
	v_mov_b32_dpp v12, v8 row_ror:8 row_mask:0xf bank_mask:0xc
	v_mov_b32_dpp v13, v9 row_ror:8 row_mask:0xf bank_mask:0xc
	v_mov_b32_dpp v14, v10 row_ror:8 row_mask:0xf bank_mask:0xc
	v_mov_b32_dpp v15, v11 row_ror:8 row_mask:0xf bank_mask:0xc
	v_mov_b32_dpp v8, v222 row_ror:8 row_mask:0xf bank_mask:0x3
	v_mov_b32_dpp v9, v223 row_ror:8 row_mask:0xf bank_mask:0x3
	v_mov_b32_dpp v10, v224 row_ror:8 row_mask:0xf bank_mask:0x3
	v_mov_b32_dpp v11, v225 row_ror:8 row_mask:0xf bank_mask:0x3
	v_mov_b32_e32 v142, v4
	v_mov_b32_e32 v143, v5
	v_mov_b32_e32 v144, v6
	v_mov_b32_e32 v145, v7
	v_mov_b32_dpp v4, v0 row_ror:8 row_mask:0xf bank_mask:0xc
	v_mov_b32_dpp v5, v1 row_ror:8 row_mask:0xf bank_mask:0xc
	v_mov_b32_dpp v6, v2 row_ror:8 row_mask:0xf bank_mask:0xc
	v_mov_b32_dpp v7, v3 row_ror:8 row_mask:0xf bank_mask:0xc
	v_mov_b32_dpp v0, v142 row_ror:8 row_mask:0xf bank_mask:0x3
	v_mov_b32_dpp v1, v143 row_ror:8 row_mask:0xf bank_mask:0x3
	v_mov_b32_dpp v2, v144 row_ror:8 row_mask:0xf bank_mask:0x3
	v_mov_b32_dpp v3, v145 row_ror:8 row_mask:0xf bank_mask:0x3
	s_waitcnt vmcnt(0)
;     __device__ __forceinline__ void operator()(const f32x4 (&acc)[2][2][4][2], const pg8::Unit& u, int wr, int wc, int fr, int fq) const {
;         const int row0 = u.pm * 256 + wr * 64 + fr; const int colb = u.pn * 256 + 32 * wc + 8 * fq;
;         if (u.nt == 0) {
; #pragma unroll
;             for (int ai = 0; ai < 2; ++ai) {
;                 f32x4 xv[4][2][2];
; #pragma unroll
;                 for (int m = 0; m < 4; ++m)
; #pragma unroll
;                     for (int bj = 0; bj < 2; ++bj) { const float* xr = out + (size_t)(row0 + ai * 128 + m * 16) * DM + colb + 128 * bj; xv[m][bj][0] = *(const f32x4*)xr; xv[m][bj][1] = *(const f32x4*)(xr + 4); }
; #pragma unroll
;                 for (int m = 0; m < 4; ++m) {
;                     float* orow = out + (size_t)(row0 + ai * 128 + m * 16) * DM;
; #pragma unroll
;                     for (int bj = 0; bj < 2; ++bj) {
;                         const int col = colb + 128 * bj;
;                         *(f32x4*)(orow + col) = acc[ai][bj][m][0] + xv[m][bj][0]; *(f32x4*)(orow + col + 4) = acc[ai][bj][m][1] + xv[m][bj][1];
;                     }
;                 }
;             }
	v_pk_add_f32 v[124:125], v[124:125], v[160:161]
	v_pk_add_f32 v[126:127], v[126:127], v[162:163]
	v_pk_add_f32 v[120:121], v[120:121], v[164:165]
	v_pk_add_f32 v[122:123], v[122:123], v[166:167]
	v_pk_add_f32 v[116:117], v[116:117], v[168:169]
	v_pk_add_f32 v[118:119], v[118:119], v[170:171]
	v_pk_add_f32 v[112:113], v[112:113], v[172:173]
	v_pk_add_f32 v[114:115], v[114:115], v[174:175]
	v_pk_add_f32 v[108:109], v[108:109], v[176:177]
	v_pk_add_f32 v[110:111], v[110:111], v[178:179]
	v_pk_add_f32 v[104:105], v[104:105], v[180:181]
	v_pk_add_f32 v[106:107], v[106:107], v[182:183]
	v_pk_add_f32 v[100:101], v[100:101], v[184:185]
	v_pk_add_f32 v[102:103], v[102:103], v[186:187]
	v_pk_add_f32 v[96:97], v[96:97], v[190:191]
	v_pk_add_f32 v[98:99], v[98:99], v[192:193]
	v_pk_add_f32 v[92:93], v[92:93], v[194:195]
	v_pk_add_f32 v[94:95], v[94:95], v[196:197]
	v_pk_add_f32 v[88:89], v[88:89], v[198:199]
	v_pk_add_f32 v[90:91], v[90:91], v[200:201]
	v_pk_add_f32 v[84:85], v[84:85], v[202:203]
	v_pk_add_f32 v[86:87], v[86:87], v[204:205]
	v_pk_add_f32 v[80:81], v[80:81], v[206:207]
	v_pk_add_f32 v[82:83], v[82:83], v[208:209]
	v_pk_add_f32 v[76:77], v[76:77], v[210:211]
	v_pk_add_f32 v[78:79], v[78:79], v[212:213]
	v_pk_add_f32 v[72:73], v[72:73], v[214:215]
	v_pk_add_f32 v[74:75], v[74:75], v[216:217]
	v_pk_add_f32 v[68:69], v[68:69], v[218:219]
	v_pk_add_f32 v[70:71], v[70:71], v[220:221]
	v_pk_add_f32 v[64:65], v[64:65], v[150:151]
	v_pk_add_f32 v[66:67], v[66:67], v[152:153]
	s_mov_b32 s4, 0x100000
	v_lshl_add_u64 v[224:225], v[146:147], 0, s[4:5]
	global_load_dwordx4 v[160:163], v[224:225], off
	global_load_dwordx4 v[168:171], v[224:225], off offset:512
	s_mov_b32 s4, 0x110000
	v_lshl_add_u64 v[226:227], v[146:147], 0, s[4:5]
	global_load_dwordx4 v[164:167], v[226:227], off
	global_load_dwordx4 v[172:175], v[226:227], off offset:512
	s_mov_b32 s4, 0x120000
	v_lshl_add_u64 v[224:225], v[146:147], 0, s[4:5]
	global_load_dwordx4 v[176:179], v[224:225], off
	global_load_dwordx4 v[184:187], v[224:225], off offset:512
	s_mov_b32 s4, 0x130000
	v_lshl_add_u64 v[226:227], v[146:147], 0, s[4:5]
	global_load_dwordx4 v[180:183], v[226:227], off
	global_load_dwordx4 v[190:193], v[226:227], off offset:512
	s_mov_b32 s4, 0x140000
	v_lshl_add_u64 v[224:225], v[146:147], 0, s[4:5]
	global_load_dwordx4 v[194:197], v[224:225], off
	global_load_dwordx4 v[202:205], v[224:225], off offset:512
	s_mov_b32 s4, 0x150000
	v_lshl_add_u64 v[226:227], v[146:147], 0, s[4:5]
	global_load_dwordx4 v[198:201], v[226:227], off
	global_load_dwordx4 v[206:209], v[226:227], off offset:512
	s_mov_b32 s4, 0x160000
	v_lshl_add_u64 v[224:225], v[146:147], 0, s[4:5]
	global_load_dwordx4 v[210:213], v[224:225], off
	global_load_dwordx4 v[218:221], v[224:225], off offset:512
	s_mov_b32 s4, 0x170000
	v_lshl_add_u64 v[226:227], v[146:147], 0, s[4:5]
	global_load_dwordx4 v[214:217], v[226:227], off
	global_load_dwordx4 v[150:153], v[226:227], off offset:512
	s_mov_b32 s4, 0x0
	v_lshl_add_u64 v[224:225], v[146:147], 0, s[4:5]
	global_store_dwordx4 v[224:225], v[124:127], off
	global_store_dwordx4 v[224:225], v[116:119], off offset:512
	s_mov_b32 s4, 0x10000
	v_lshl_add_u64 v[226:227], v[146:147], 0, s[4:5]
	global_store_dwordx4 v[226:227], v[120:123], off
	global_store_dwordx4 v[226:227], v[112:115], off offset:512
	s_mov_b32 s4, 0x20000
	v_lshl_add_u64 v[224:225], v[146:147], 0, s[4:5]
	global_store_dwordx4 v[224:225], v[108:111], off
	global_store_dwordx4 v[224:225], v[100:103], off offset:512
	s_mov_b32 s4, 0x30000
	v_lshl_add_u64 v[226:227], v[146:147], 0, s[4:5]
	global_store_dwordx4 v[226:227], v[104:107], off
	global_store_dwordx4 v[226:227], v[96:99], off offset:512
	s_mov_b32 s4, 0x40000
	v_lshl_add_u64 v[224:225], v[146:147], 0, s[4:5]
	global_store_dwordx4 v[224:225], v[92:95], off
	global_store_dwordx4 v[224:225], v[84:87], off offset:512
	s_mov_b32 s4, 0x50000
	v_lshl_add_u64 v[226:227], v[146:147], 0, s[4:5]
	global_store_dwordx4 v[226:227], v[88:91], off
	global_store_dwordx4 v[226:227], v[80:83], off offset:512
	s_mov_b32 s4, 0x60000
	v_lshl_add_u64 v[224:225], v[146:147], 0, s[4:5]
	global_store_dwordx4 v[224:225], v[76:79], off
	global_store_dwordx4 v[224:225], v[68:71], off offset:512
	s_mov_b32 s4, 0x70000
	v_lshl_add_u64 v[226:227], v[146:147], 0, s[4:5]
	global_store_dwordx4 v[226:227], v[72:75], off
	global_store_dwordx4 v[226:227], v[64:67], off offset:512
	s_waitcnt vmcnt(16)
;     __device__ __forceinline__ void operator()(const f32x4 (&acc)[2][2][4][2], const pg8::Unit& u, int wr, int wc, int fr, int fq) const {
;         const int row0 = u.pm * 256 + wr * 64 + fr; const int colb = u.pn * 256 + 32 * wc + 8 * fq;
;         if (u.nt == 0) {
; #pragma unroll
;             for (int ai = 0; ai < 2; ++ai) {
;                 f32x4 xv[4][2][2];
; #pragma unroll
;                 for (int m = 0; m < 4; ++m)
; #pragma unroll
;                     for (int bj = 0; bj < 2; ++bj) { const float* xr = out + (size_t)(row0 + ai * 128 + m * 16) * DM + colb + 128 * bj; xv[m][bj][0] = *(const f32x4*)xr; xv[m][bj][1] = *(const f32x4*)(xr + 4); }
; #pragma unroll
;                 for (int m = 0; m < 4; ++m) {
;                     float* orow = out + (size_t)(row0 + ai * 128 + m * 16) * DM;
; #pragma unroll
;                     for (int bj = 0; bj < 2; ++bj) {
;                         const int col = colb + 128 * bj;
;                         *(f32x4*)(orow + col) = acc[ai][bj][m][0] + xv[m][bj][0]; *(f32x4*)(orow + col + 4) = acc[ai][bj][m][1] + xv[m][bj][1];
;                     }
;                 }
;             }
	v_pk_add_f32 v[60:61], v[60:61], v[160:161]
	v_pk_add_f32 v[62:63], v[62:63], v[162:163]
	v_pk_add_f32 v[56:57], v[56:57], v[164:165]
	v_pk_add_f32 v[58:59], v[58:59], v[166:167]
	v_pk_add_f32 v[52:53], v[52:53], v[168:169]
	v_pk_add_f32 v[54:55], v[54:55], v[170:171]
	v_pk_add_f32 v[48:49], v[48:49], v[172:173]
	v_pk_add_f32 v[50:51], v[50:51], v[174:175]
	v_pk_add_f32 v[44:45], v[44:45], v[176:177]
	v_pk_add_f32 v[46:47], v[46:47], v[178:179]
	v_pk_add_f32 v[40:41], v[40:41], v[180:181]
	v_pk_add_f32 v[42:43], v[42:43], v[182:183]
	v_pk_add_f32 v[36:37], v[36:37], v[184:185]
	v_pk_add_f32 v[38:39], v[38:39], v[186:187]
	v_pk_add_f32 v[32:33], v[32:33], v[190:191]
	v_pk_add_f32 v[34:35], v[34:35], v[192:193]
	v_pk_add_f32 v[28:29], v[28:29], v[194:195]
	v_pk_add_f32 v[30:31], v[30:31], v[196:197]
	v_pk_add_f32 v[24:25], v[24:25], v[198:199]
	v_pk_add_f32 v[26:27], v[26:27], v[200:201]
	v_pk_add_f32 v[20:21], v[20:21], v[202:203]
	v_pk_add_f32 v[22:23], v[22:23], v[204:205]
	v_pk_add_f32 v[16:17], v[16:17], v[206:207]
	v_pk_add_f32 v[18:19], v[18:19], v[208:209]
	v_pk_add_f32 v[12:13], v[12:13], v[210:211]
	v_pk_add_f32 v[14:15], v[14:15], v[212:213]
	v_pk_add_f32 v[8:9], v[8:9], v[214:215]
	v_pk_add_f32 v[10:11], v[10:11], v[216:217]
	v_pk_add_f32 v[4:5], v[4:5], v[218:219]
	v_pk_add_f32 v[6:7], v[6:7], v[220:221]
	v_pk_add_f32 v[0:1], v[0:1], v[150:151]
	v_pk_add_f32 v[2:3], v[2:3], v[152:153]
	s_mov_b32 s4, 0x100000
	v_lshl_add_u64 v[224:225], v[146:147], 0, s[4:5]
	global_store_dwordx4 v[224:225], v[60:63], off
	global_store_dwordx4 v[224:225], v[52:55], off offset:512
	s_mov_b32 s4, 0x110000
	v_lshl_add_u64 v[226:227], v[146:147], 0, s[4:5]
	global_store_dwordx4 v[226:227], v[56:59], off
	global_store_dwordx4 v[226:227], v[48:51], off offset:512
	s_mov_b32 s4, 0x120000
	v_lshl_add_u64 v[224:225], v[146:147], 0, s[4:5]
	global_store_dwordx4 v[224:225], v[44:47], off
	global_store_dwordx4 v[224:225], v[36:39], off offset:512
	s_mov_b32 s4, 0x130000
	v_lshl_add_u64 v[226:227], v[146:147], 0, s[4:5]
	global_store_dwordx4 v[226:227], v[40:43], off
	global_store_dwordx4 v[226:227], v[32:35], off offset:512
	s_mov_b32 s4, 0x140000
	v_lshl_add_u64 v[224:225], v[146:147], 0, s[4:5]
	global_store_dwordx4 v[224:225], v[28:31], off
	global_store_dwordx4 v[224:225], v[20:23], off offset:512
	s_mov_b32 s4, 0x150000
	v_lshl_add_u64 v[226:227], v[146:147], 0, s[4:5]
	global_store_dwordx4 v[226:227], v[24:27], off
	global_store_dwordx4 v[226:227], v[16:19], off offset:512
	s_mov_b32 s4, 0x160000
	v_lshl_add_u64 v[224:225], v[146:147], 0, s[4:5]
	global_store_dwordx4 v[224:225], v[12:15], off
	global_store_dwordx4 v[224:225], v[4:7], off offset:512
	s_mov_b32 s4, 0x170000
	v_lshl_add_u64 v[226:227], v[146:147], 0, s[4:5]
	global_store_dwordx4 v[226:227], v[8:11], off
	global_store_dwordx4 v[226:227], v[0:3], off offset:512
	v_readlane_b32 s4, v254, 16
	v_readlane_b32 s5, v254, 17
	v_readlane_b32 s6, v254, 18
	v_readlane_b32 s7, v254, 19
	v_readlane_b32 s8, v254, 20
	v_readlane_b32 s9, v254, 21
	v_readlane_b32 s10, v254, 22
	v_readlane_b32 s11, v254, 23
	v_readlane_b32 s12, v254, 24
	v_readlane_b32 s13, v254, 25
	v_readlane_b32 s14, v254, 26
	v_readlane_b32 s15, v254, 27
	v_readlane_b32 s16, v254, 28
	v_readlane_b32 s17, v254, 29
	s_and_b64 vcc, exec, s[2:3]
	s_mov_b64 s[2:3], -1
	s_cbranch_vccnz .LBB0_784
